# no per-phase s_setprio toggles in the GEMM loops plus list-scheduled SwiGLU epilogue with accumulator zeroing folded in
# speedup vs baseline: 1.0111x; 1.0015x over previous
; #define PG8_STAGE(bufoff, gbase, voff) do { _Pragma("unroll") for (int _i = 0; _i < 2; ++_i) \
;         __builtin_amdgcn_global_load_lds((const unsigned*)((const char*)(gbase) + (voff)[_i]), (PG8_LAS unsigned*)(lds + (bufoff) + ldsw + _i * 8192), 16, 0, 0); } while (0)
; #define PG8_LDA(dst, b, h) do { int aoff; asm volatile("v_add_u32 %0, %1, %2" : "=v"(aoff) : "s"(ua), "v"(foff)); _Pragma("unroll") for (int m = 0; m < 4; ++m) _Pragma("unroll") for (int k = 0; k < 2; ++k) dst[m][k] = *(const PG8_LAS bf16x8*)(lds + PG8_SA(b, h) + aoff + m * 2048 + k * 1024); } while (0)
; #define PG8_LDB(dst, b, h) do { int boff; asm volatile("v_add_u32 %0, %1, %2" : "=v"(boff) : "s"(ub), "v"(foff)); _Pragma("unroll") for (int n = 0; n < 2; ++n) _Pragma("unroll") for (int k = 0; k < 2; ++k) dst[n][k] = *(const PG8_LAS bf16x8*)(lds + PG8_SB(b, h) + boff + n * 2048 + k * 1024); } while (0)
; #define PG8_MMA(ai, bj, At, Bt) do { __builtin_amdgcn_s_setprio(1); _Pragma("unroll") for (int m = 0; m < 4; ++m) _Pragma("unroll") for (int n = 0; n < 2; ++n) _Pragma("unroll") for (int k = 0; k < 2; ++k) \
;         acc[ai][bj][m][n] = __builtin_amdgcn_mfma_f32_16x16x32_bf16(Bt[n][k], At[m][k], acc[ai][bj][m][n], 0, 0, 0); __builtin_amdgcn_s_setprio(0); } while (0)
; #define PG8_WAIT_L(n) asm volatile("s_waitcnt lgkmcnt(" #n ")" ::: "memory")
; #define PG8_BAR __builtin_amdgcn_s_barrier()
; template <class Epi, class Sched>
; __device__ __forceinline__ void gemm_phase(PG8_LAS unsigned char* lds, const Gemm g, const Sched& S, const Epi& E) {
;     ...
;             const bool last = (t == cnt - 2);
;             const char* a1 = cA + (size_t)(t + 1) * kstep;
;             const char* a2 = last ? nA : cA + (size_t)(t + 2) * kstep; const char* b2 = last ? nB : cB + (size_t)(t + 2) * kstep;
;             const char* a3 = a2 + kstep; const char* b3 = b2 + kstep;
;             if (last && has_next) S.a_ready(nxt);
;             PG8_LDB(B0, 0, 0); PG8_SCHED; PG8_LDA(At, 0, 0); PG8_STAGE(PG8_SA(1, 1), a1 + hstep, voffA);
;             PG8_WAIT_L(8); PG8_BAR; PG8_WAIT_L(0); PG8_MMA(0, 0, At, B0); PG8_BAR; PG8_SCHED;
;             PG8_LDB(B1, 0, 1); PG8_STAGE(PG8_SB(0, 0), b2, voffB);
;             PG8_BAR; PG8_WAIT_L(0); PG8_MMA(0, 1, At, B1); PG8_BAR;
;             PG8_LDA(At, 0, 1); PG8_STAGE(PG8_SA(0, 0), a2, voffA);
;             PG8_BAR; PG8_WAIT_L(0); PG8_MMA(1, 0, At, B0); PG8_BAR; PG8_SCHED;
.Lp7_zero_skip:
.LBB0_1109:
	s_add_u32 s44, s26, 0xfffc0080
	s_addc_u32 s45, s27, -1
	s_add_i32 s75, 0, 0x10000
	v_add_u32 v142, s51, v1
	s_cmp_eq_u32 s74, 12
	v_add_u32_e32 v158, s75, v142
	ds_read_b128 v[142:145], v158
	ds_read_b128 v[146:149], v158 offset:1024
	ds_read_b128 v[150:153], v158 offset:2048
	ds_read_b128 v[158:161], v158 offset:3072
	s_cselect_b32 s47, s5, s45
	s_cselect_b32 s46, s21, s44
	s_cselect_b32 s45, s19, s63
	s_cselect_b32 s44, s61, s62
	v_add_u32 v162, s50, v1
	v_lshl_add_u64 v[194:195], s[26:27], 0, v[138:139]
	v_add_u32_e32 v190, 0, v162
	s_add_i32 m0, s3, 0xc000
	ds_read_b128 v[162:165], v190
	ds_read_b128 v[166:169], v190 offset:1024
	ds_read_b128 v[170:173], v190 offset:2048
	ds_read_b128 v[174:177], v190 offset:3072
	ds_read_b128 v[178:181], v190 offset:4096
	ds_read_b128 v[182:185], v190 offset:5120
	ds_read_b128 v[186:189], v190 offset:6144
	ds_read_b128 v[190:193], v190 offset:7168
	global_load_lds_dwordx4 v[194:195], off
	v_lshl_add_u64 v[194:195], s[26:27], 0, v[140:141]
	s_add_i32 m0, s3, 0xe000
	s_nop 0
	global_load_lds_dwordx4 v[194:195], off
	s_waitcnt lgkmcnt(8)
	s_barrier
	s_waitcnt lgkmcnt(0)
	s_waitcnt lgkmcnt(0)
	v_mfma_f32_16x16x32_bf16 v[126:129], v[142:145], v[162:165], v[126:129]
	v_mfma_f32_16x16x32_bf16 v[118:121], v[150:153], v[162:165], v[118:121]
	v_mfma_f32_16x16x32_bf16 v[110:113], v[142:145], v[170:173], v[110:113]
	v_mfma_f32_16x16x32_bf16 v[102:105], v[150:153], v[170:173], v[102:105]
	v_mfma_f32_16x16x32_bf16 v[94:97], v[142:145], v[178:181], v[94:97]
	v_mfma_f32_16x16x32_bf16 v[86:89], v[150:153], v[178:181], v[86:89]
	v_mfma_f32_16x16x32_bf16 v[78:81], v[142:145], v[186:189], v[78:81]
	v_mfma_f32_16x16x32_bf16 v[70:73], v[150:153], v[186:189], v[70:73]
	v_mfma_f32_16x16x32_bf16 v[126:129], v[146:149], v[166:169], v[126:129]
	v_mfma_f32_16x16x32_bf16 v[118:121], v[158:161], v[166:169], v[118:121]
	v_mfma_f32_16x16x32_bf16 v[110:113], v[146:149], v[174:177], v[110:113]
	v_mfma_f32_16x16x32_bf16 v[102:105], v[158:161], v[174:177], v[102:105]
	v_mfma_f32_16x16x32_bf16 v[94:97], v[146:149], v[182:185], v[94:97]
	v_mfma_f32_16x16x32_bf16 v[86:89], v[158:161], v[182:185], v[86:89]
	v_mfma_f32_16x16x32_bf16 v[78:81], v[146:149], v[190:193], v[78:81]
	v_mfma_f32_16x16x32_bf16 v[70:73], v[158:161], v[190:193], v[70:73]
	s_barrier
	s_add_i32 s78, 0, 0x14000
	s_add_i32 s75, s75, s11
	v_add_u32 v194, s51, v1
	v_lshl_add_u64 v[212:213], s[44:45], 0, v[134:135]
	v_add_u32_e32 v206, s78, v194
	s_mov_b32 m0, s75
	ds_read_b128 v[194:197], v206
	ds_read_b128 v[198:201], v206 offset:1024
	ds_read_b128 v[202:205], v206 offset:2048
	ds_read_b128 v[206:209], v206 offset:3072
	global_load_lds_dwordx4 v[212:213], off
	v_lshl_add_u64 v[214:215], s[44:45], 0, v[130:131]
	s_add_i32 m0, s75, 0x2000
	s_nop 0
	global_load_lds_dwordx4 v[214:215], off
	s_barrier
	s_waitcnt lgkmcnt(0)
	s_waitcnt lgkmcnt(0)
	v_mfma_f32_16x16x32_bf16 v[122:125], v[194:197], v[162:165], v[122:125]
	v_mfma_f32_16x16x32_bf16 v[114:117], v[202:205], v[162:165], v[114:117]
	v_mfma_f32_16x16x32_bf16 v[106:109], v[194:197], v[170:173], v[106:109]
	v_mfma_f32_16x16x32_bf16 v[98:101], v[202:205], v[170:173], v[98:101]
	v_mfma_f32_16x16x32_bf16 v[90:93], v[194:197], v[178:181], v[90:93]
	v_mfma_f32_16x16x32_bf16 v[82:85], v[202:205], v[178:181], v[82:85]
	v_mfma_f32_16x16x32_bf16 v[74:77], v[194:197], v[186:189], v[74:77]
	v_mfma_f32_16x16x32_bf16 v[66:69], v[202:205], v[186:189], v[66:69]
	v_mfma_f32_16x16x32_bf16 v[122:125], v[198:201], v[166:169], v[122:125]
	v_mfma_f32_16x16x32_bf16 v[114:117], v[206:209], v[166:169], v[114:117]
	v_mfma_f32_16x16x32_bf16 v[106:109], v[198:201], v[174:177], v[106:109]
	v_mfma_f32_16x16x32_bf16 v[98:101], v[206:209], v[174:177], v[98:101]
	v_mfma_f32_16x16x32_bf16 v[90:93], v[198:201], v[182:185], v[90:93]
	v_mfma_f32_16x16x32_bf16 v[82:85], v[206:209], v[182:185], v[82:85]
	v_mfma_f32_16x16x32_bf16 v[74:77], v[198:201], v[190:193], v[74:77]
	v_mfma_f32_16x16x32_bf16 v[66:69], v[206:209], v[190:193], v[66:69]
	s_mov_b32 m0, s3
	s_barrier
	v_add_u32 v162, s50, v1
	v_lshl_add_u64 v[218:219], s[46:47], 0, v[136:137]
	v_add_u32_e32 v190, 0, v162
	ds_read_b128 v[162:165], v190 offset:16384
	ds_read_b128 v[166:169], v190 offset:17408
	ds_read_b128 v[170:173], v190 offset:18432
	ds_read_b128 v[174:177], v190 offset:19456
	ds_read_b128 v[178:181], v190 offset:20480
	ds_read_b128 v[182:185], v190 offset:21504
	ds_read_b128 v[186:189], v190 offset:22528
	ds_read_b128 v[190:193], v190 offset:23552
	global_load_lds_dwordx4 v[218:219], off
	v_lshl_add_u64 v[220:221], s[46:47], 0, v[132:133]
	s_mov_b32 m0, s17
	s_nop 0
	global_load_lds_dwordx4 v[220:221], off
	s_barrier
	s_waitcnt lgkmcnt(0)
	s_waitcnt lgkmcnt(0)
	v_mfma_f32_16x16x32_bf16 v[62:65], v[142:145], v[162:165], v[62:65]
	v_mfma_f32_16x16x32_bf16 v[54:57], v[150:153], v[162:165], v[54:57]
	v_mfma_f32_16x16x32_bf16 v[46:49], v[142:145], v[170:173], v[46:49]
	v_mfma_f32_16x16x32_bf16 v[38:41], v[150:153], v[170:173], v[38:41]
	v_mfma_f32_16x16x32_bf16 v[30:33], v[142:145], v[178:181], v[30:33]
	v_mfma_f32_16x16x32_bf16 v[22:25], v[150:153], v[178:181], v[22:25]
	v_mfma_f32_16x16x32_bf16 v[14:17], v[142:145], v[186:189], v[14:17]
	v_mfma_f32_16x16x32_bf16 v[6:9], v[150:153], v[186:189], v[6:9]
	v_mfma_f32_16x16x32_bf16 v[62:65], v[146:149], v[166:169], v[62:65]
	v_mfma_f32_16x16x32_bf16 v[54:57], v[158:161], v[166:169], v[54:57]
	v_mfma_f32_16x16x32_bf16 v[46:49], v[146:149], v[174:177], v[46:49]
	v_mfma_f32_16x16x32_bf16 v[38:41], v[158:161], v[174:177], v[38:41]
	v_mfma_f32_16x16x32_bf16 v[30:33], v[146:149], v[182:185], v[30:33]
	v_mfma_f32_16x16x32_bf16 v[22:25], v[158:161], v[182:185], v[22:25]
	v_mfma_f32_16x16x32_bf16 v[14:17], v[146:149], v[190:193], v[14:17]
	v_mfma_f32_16x16x32_bf16 v[6:9], v[158:161], v[190:193], v[6:9]
	s_barrier
; #define PG8_STAGE(bufoff, gbase, voff) do { _Pragma("unroll") for (int _i = 0; _i < 2; ++_i) \
;         __builtin_amdgcn_global_load_lds((const unsigned*)((const char*)(gbase) + (voff)[_i]), (PG8_LAS unsigned*)(lds + (bufoff) + ldsw + _i * 8192), 16, 0, 0); } while (0)
; #define PG8_LDA(dst, b, h) do { int aoff; asm volatile("v_add_u32 %0, %1, %2" : "=v"(aoff) : "s"(ua), "v"(foff)); _Pragma("unroll") for (int m = 0; m < 4; ++m) _Pragma("unroll") for (int k = 0; k < 2; ++k) dst[m][k] = *(const PG8_LAS bf16x8*)(lds + PG8_SA(b, h) + aoff + m * 2048 + k * 1024); } while (0)
; #define PG8_LDB(dst, b, h) do { int boff; asm volatile("v_add_u32 %0, %1, %2" : "=v"(boff) : "s"(ub), "v"(foff)); _Pragma("unroll") for (int n = 0; n < 2; ++n) _Pragma("unroll") for (int k = 0; k < 2; ++k) dst[n][k] = *(const PG8_LAS bf16x8*)(lds + PG8_SB(b, h) + boff + n * 2048 + k * 1024); } while (0)
; #define PG8_MMA(ai, bj, At, Bt) do { __builtin_amdgcn_s_setprio(1); _Pragma("unroll") for (int m = 0; m < 4; ++m) _Pragma("unroll") for (int n = 0; n < 2; ++n) _Pragma("unroll") for (int k = 0; k < 2; ++k) \
;         acc[ai][bj][m][n] = __builtin_amdgcn_mfma_f32_16x16x32_bf16(Bt[n][k], At[m][k], acc[ai][bj][m][n], 0, 0, 0); __builtin_amdgcn_s_setprio(0); } while (0)
; #define PG8_WAIT_V(n) asm volatile("s_waitcnt vmcnt(" #n ")" ::: "memory")
; #define PG8_WAIT_L(n) asm volatile("s_waitcnt lgkmcnt(" #n ")" ::: "memory")
; #define PG8_BAR __builtin_amdgcn_s_barrier()
; #define PG8_SCHED __builtin_amdgcn_sched_barrier(0)
; template <class Epi, class Sched>
; __device__ __forceinline__ void gemm_phase(PG8_LAS unsigned char* lds, const Gemm g, const Sched& S, const Epi& E) {
;     ...
;             PG8_STAGE(PG8_SB(0, 1), b2 + hstep, voffB);
;             PG8_WAIT_V(6); PG8_BAR; PG8_MMA(1, 1, At, B1); PG8_BAR;
;             PG8_LDB(B0, 1, 0); PG8_SCHED; PG8_LDA(At, 1, 0); PG8_STAGE(PG8_SA(0, 1), a2 + hstep, voffA);
;             PG8_WAIT_L(8); PG8_BAR; PG8_WAIT_L(0); PG8_MMA(0, 0, At, B0); PG8_BAR; PG8_SCHED;
;             PG8_LDB(B1, 1, 1); PG8_STAGE(PG8_SB(1, 0), b3, voffB);
;             PG8_BAR; PG8_WAIT_L(0); PG8_MMA(0, 1, At, B1); PG8_BAR;
	s_add_u32 s76, s44, 0x40000
	s_addc_u32 s77, s45, 0
	s_add_i32 s75, s78, s11
	v_lshl_add_u64 v[142:143], s[76:77], 0, v[134:135]
	s_mov_b32 m0, s75
	s_nop 0
	global_load_lds_dwordx4 v[142:143], off
	v_lshl_add_u64 v[142:143], s[76:77], 0, v[130:131]
	s_add_i32 m0, s75, 0x2000
	s_nop 0
	global_load_lds_dwordx4 v[142:143], off
	s_waitcnt vmcnt(6)
	s_barrier
	v_mfma_f32_16x16x32_bf16 v[58:61], v[194:197], v[162:165], v[58:61]
	v_mfma_f32_16x16x32_bf16 v[50:53], v[202:205], v[162:165], v[50:53]
	v_mfma_f32_16x16x32_bf16 v[42:45], v[194:197], v[170:173], v[42:45]
	v_mfma_f32_16x16x32_bf16 v[34:37], v[202:205], v[170:173], v[34:37]
	v_mfma_f32_16x16x32_bf16 v[26:29], v[194:197], v[178:181], v[26:29]
	v_mfma_f32_16x16x32_bf16 v[18:21], v[202:205], v[178:181], v[18:21]
	v_mfma_f32_16x16x32_bf16 v[10:13], v[194:197], v[186:189], v[10:13]
	v_mfma_f32_16x16x32_bf16 v[2:5], v[202:205], v[186:189], v[2:5]
	v_mfma_f32_16x16x32_bf16 v[58:61], v[198:201], v[166:169], v[58:61]
	v_mfma_f32_16x16x32_bf16 v[50:53], v[206:209], v[166:169], v[50:53]
	v_mfma_f32_16x16x32_bf16 v[42:45], v[198:201], v[174:177], v[42:45]
	v_mfma_f32_16x16x32_bf16 v[34:37], v[206:209], v[174:177], v[34:37]
	v_mfma_f32_16x16x32_bf16 v[26:29], v[198:201], v[182:185], v[26:29]
	v_mfma_f32_16x16x32_bf16 v[18:21], v[206:209], v[182:185], v[18:21]
	v_mfma_f32_16x16x32_bf16 v[10:13], v[198:201], v[190:193], v[10:13]
	v_mfma_f32_16x16x32_bf16 v[2:5], v[206:209], v[190:193], v[2:5]
	s_add_i32 s75, 0, 0x18000
	s_barrier
	v_add_u32 v142, s51, v1
	s_nop 0
	v_add_u32_e32 v158, s75, v142
	ds_read_b128 v[142:145], v158
	ds_read_b128 v[146:149], v158 offset:1024
	ds_read_b128 v[150:153], v158 offset:2048
	ds_read_b128 v[158:161], v158 offset:3072
	s_add_u32 s46, s46, 0x40000
	s_addc_u32 s47, s47, 0
	s_mov_b32 m0, s48
	v_add_u32 v162, s50, v1
	v_lshl_add_u64 v[194:195], s[46:47], 0, v[136:137]
	v_add_u32_e32 v190, 0, v162
	ds_read_b128 v[162:165], v190 offset:32768
	ds_read_b128 v[166:169], v190 offset:33792
	ds_read_b128 v[170:173], v190 offset:34816
	ds_read_b128 v[174:177], v190 offset:35840
	ds_read_b128 v[178:181], v190 offset:36864
	ds_read_b128 v[182:185], v190 offset:37888
	ds_read_b128 v[186:189], v190 offset:38912
	ds_read_b128 v[190:193], v190 offset:39936
	global_load_lds_dwordx4 v[194:195], off
	v_lshl_add_u64 v[194:195], s[46:47], 0, v[132:133]
	s_mov_b32 m0, s49
	s_nop 0
	global_load_lds_dwordx4 v[194:195], off
	s_waitcnt lgkmcnt(8)
	s_barrier
	s_waitcnt lgkmcnt(0)
	s_waitcnt lgkmcnt(0)
	v_mfma_f32_16x16x32_bf16 v[126:129], v[142:145], v[162:165], v[126:129]
	v_mfma_f32_16x16x32_bf16 v[118:121], v[150:153], v[162:165], v[118:121]
	v_mfma_f32_16x16x32_bf16 v[110:113], v[142:145], v[170:173], v[110:113]
	v_mfma_f32_16x16x32_bf16 v[102:105], v[150:153], v[170:173], v[102:105]
	v_mfma_f32_16x16x32_bf16 v[94:97], v[142:145], v[178:181], v[94:97]
	v_mfma_f32_16x16x32_bf16 v[86:89], v[150:153], v[178:181], v[86:89]
	v_mfma_f32_16x16x32_bf16 v[78:81], v[142:145], v[186:189], v[78:81]
	v_mfma_f32_16x16x32_bf16 v[70:73], v[150:153], v[186:189], v[70:73]
	v_mfma_f32_16x16x32_bf16 v[126:129], v[146:149], v[166:169], v[126:129]
	v_mfma_f32_16x16x32_bf16 v[118:121], v[158:161], v[166:169], v[118:121]
	v_mfma_f32_16x16x32_bf16 v[110:113], v[146:149], v[174:177], v[110:113]
	v_mfma_f32_16x16x32_bf16 v[102:105], v[158:161], v[174:177], v[102:105]
	v_mfma_f32_16x16x32_bf16 v[94:97], v[146:149], v[182:185], v[94:97]
	v_mfma_f32_16x16x32_bf16 v[86:89], v[158:161], v[182:185], v[86:89]
	v_mfma_f32_16x16x32_bf16 v[78:81], v[146:149], v[190:193], v[78:81]
	v_mfma_f32_16x16x32_bf16 v[70:73], v[158:161], v[190:193], v[70:73]
	s_barrier
	s_add_i32 s46, 0, 0x1c000
	s_add_i32 s47, s75, s11
	v_add_u32 v194, s51, v1
	v_lshl_add_u64 v[212:213], v[212:213], 0, s[30:31]
	v_add_u32_e32 v206, s46, v194
	s_mov_b32 m0, s47
	ds_read_b128 v[194:197], v206
	ds_read_b128 v[198:201], v206 offset:1024
	ds_read_b128 v[202:205], v206 offset:2048
	ds_read_b128 v[206:209], v206 offset:3072
	global_load_lds_dwordx4 v[212:213], off
	v_lshl_add_u64 v[212:213], v[214:215], 0, s[30:31]
	s_add_i32 m0, s47, 0x2000
	s_nop 0
	global_load_lds_dwordx4 v[212:213], off
	s_barrier
	s_waitcnt lgkmcnt(0)
	s_waitcnt lgkmcnt(0)
	v_mfma_f32_16x16x32_bf16 v[122:125], v[194:197], v[162:165], v[122:125]
	v_mfma_f32_16x16x32_bf16 v[114:117], v[202:205], v[162:165], v[114:117]
	v_mfma_f32_16x16x32_bf16 v[106:109], v[194:197], v[170:173], v[106:109]
	v_mfma_f32_16x16x32_bf16 v[98:101], v[202:205], v[170:173], v[98:101]
	v_mfma_f32_16x16x32_bf16 v[90:93], v[194:197], v[178:181], v[90:93]
	v_mfma_f32_16x16x32_bf16 v[82:85], v[202:205], v[178:181], v[82:85]
	v_mfma_f32_16x16x32_bf16 v[74:77], v[194:197], v[186:189], v[74:77]
	v_mfma_f32_16x16x32_bf16 v[66:69], v[202:205], v[186:189], v[66:69]
	v_mfma_f32_16x16x32_bf16 v[122:125], v[198:201], v[166:169], v[122:125]
	v_mfma_f32_16x16x32_bf16 v[114:117], v[206:209], v[166:169], v[114:117]
	v_mfma_f32_16x16x32_bf16 v[106:109], v[198:201], v[174:177], v[106:109]
	v_mfma_f32_16x16x32_bf16 v[98:101], v[206:209], v[174:177], v[98:101]
	v_mfma_f32_16x16x32_bf16 v[90:93], v[198:201], v[182:185], v[90:93]
	v_mfma_f32_16x16x32_bf16 v[82:85], v[206:209], v[182:185], v[82:85]
	v_mfma_f32_16x16x32_bf16 v[74:77], v[198:201], v[190:193], v[74:77]
	v_mfma_f32_16x16x32_bf16 v[66:69], v[206:209], v[190:193], v[66:69]
	s_mov_b32 m0, s52
	s_barrier
; __device__ __forceinline__ unsigned cvt_pk_bf16(float lo, float hi) { const f32x2c f = {lo, hi}; return __builtin_bit_cast(unsigned, __builtin_convertvector(f, bf16x2c)); }
; __device__ __forceinline__ float silu_f(float g) { return g * __builtin_amdgcn_rcpf(1.0f + __expf(-g)); }
; #define PG8_STAGE(bufoff, gbase, voff) do { _Pragma("unroll") for (int _i = 0; _i < 2; ++_i) \
;         __builtin_amdgcn_global_load_lds((const unsigned*)((const char*)(gbase) + (voff)[_i]), (PG8_LAS unsigned*)(lds + (bufoff) + ldsw + _i * 8192), 16, 0, 0); } while (0)
; #define PG8_LDA(dst, b, h) do { int aoff; asm volatile("v_add_u32 %0, %1, %2" : "=v"(aoff) : "s"(ua), "v"(foff)); _Pragma("unroll") for (int m = 0; m < 4; ++m) _Pragma("unroll") for (int k = 0; k < 2; ++k) dst[m][k] = *(const PG8_LAS bf16x8*)(lds + PG8_SA(b, h) + aoff + m * 2048 + k * 1024); } while (0)
; #define PG8_WAIT_V(n) asm volatile("s_waitcnt vmcnt(" #n ")" ::: "memory")
; #define PG8_WAIT_L(n) asm volatile("s_waitcnt lgkmcnt(" #n ")" ::: "memory")
;     __device__ __forceinline__ void operator()(const f32x4 (&acc)[2][2][4][2], const Unit& u, int wr, int wc, int fr, int fq) const {
;         const int row0 = u.pm * BM + wr * 64 + fr; const int col0 = u.pn * HALF + wc * 32 + 8 * fq;
; #pragma unroll
;         for (int ai = 0; ai < 2; ++ai)
; #pragma unroll
;             for (int m = 0; m < 4; ++m) { bf16_t* rowp = H + (size_t)(row0 + ai * HALF + m * 16) * ldh + col0;
;                 const f32x4 g0 = acc[ai][0][m][0], g1 = acc[ai][0][m][1], u0 = acc[ai][1][m][0], u1 = acc[ai][1][m][1];
;                 u32x4 w; w.x = cvt_pk_bf16(silu_f(g0[0]) * u0[0], silu_f(g0[1]) * u0[1]); w.y = cvt_pk_bf16(silu_f(g0[2]) * u0[2], silu_f(g0[3]) * u0[3]);
;                 w.z = cvt_pk_bf16(silu_f(g1[0]) * u1[0], silu_f(g1[1]) * u1[1]); w.w = cvt_pk_bf16(silu_f(g1[2]) * u1[2], silu_f(g1[3]) * u1[3]);
;                 *(u32x4*)rowp = w; }
; template <class Epi, class Sched>
; __device__ __forceinline__ void gemm_phase(PG8_LAS unsigned char* lds, const Gemm g, const Sched& S, const Epi& E) {
;     ...
;             PG8_LDA(At, 1, 1); PG8_STAGE(PG8_SA(1, 0), a3, voffA);
;             PG8_BAR; PG8_WAIT_L(0); PG8_MMA(1, 0, At, B0); PG8_BAR; PG8_SCHED;
;             PG8_STAGE(PG8_SB(1, 1), b3 + hstep, voffB);
;             PG8_WAIT_V(6); PG8_BAR; PG8_MMA(1, 1, At, B1); PG8_BAR;
;         }
	v_add_u32 v162, s50, v1
	v_lshl_add_u64 v[212:213], v[218:219], 0, s[30:31]
	v_add_u32_e32 v190, 0, v162
	ds_read_b128 v[162:165], v190 offset:49152
	ds_read_b128 v[166:169], v190 offset:50176
	ds_read_b128 v[170:173], v190 offset:51200
	ds_read_b128 v[174:177], v190 offset:52224
	ds_read_b128 v[178:181], v190 offset:53248
	ds_read_b128 v[182:185], v190 offset:54272
	ds_read_b128 v[186:189], v190 offset:55296
	ds_read_b128 v[190:193], v190 offset:56320
	global_load_lds_dwordx4 v[212:213], off
	v_lshl_add_u64 v[212:213], v[220:221], 0, s[30:31]
	s_mov_b32 m0, s53
	s_nop 0
	global_load_lds_dwordx4 v[212:213], off
	s_barrier
	s_waitcnt lgkmcnt(0)
	s_waitcnt lgkmcnt(0)
	v_mfma_f32_16x16x32_bf16 v[62:65], v[142:145], v[162:165], v[62:65]
	v_mfma_f32_16x16x32_bf16 v[54:57], v[150:153], v[162:165], v[54:57]
	v_mfma_f32_16x16x32_bf16 v[46:49], v[142:145], v[170:173], v[46:49]
	v_mfma_f32_16x16x32_bf16 v[38:41], v[150:153], v[170:173], v[38:41]
	v_mfma_f32_16x16x32_bf16 v[30:33], v[142:145], v[178:181], v[30:33]
	v_mfma_f32_16x16x32_bf16 v[22:25], v[150:153], v[178:181], v[22:25]
	v_mfma_f32_16x16x32_bf16 v[14:17], v[142:145], v[186:189], v[14:17]
	v_mfma_f32_16x16x32_bf16 v[6:9], v[150:153], v[186:189], v[6:9]
	v_mfma_f32_16x16x32_bf16 v[62:65], v[146:149], v[166:169], v[62:65]
	v_mfma_f32_16x16x32_bf16 v[54:57], v[158:161], v[166:169], v[54:57]
	v_mfma_f32_16x16x32_bf16 v[46:49], v[146:149], v[174:177], v[46:49]
	v_mfma_f32_16x16x32_bf16 v[38:41], v[158:161], v[174:177], v[38:41]
	v_mfma_f32_16x16x32_bf16 v[30:33], v[146:149], v[182:185], v[30:33]
	v_mfma_f32_16x16x32_bf16 v[22:25], v[158:161], v[182:185], v[22:25]
	v_mfma_f32_16x16x32_bf16 v[14:17], v[146:149], v[190:193], v[14:17]
	v_mfma_f32_16x16x32_bf16 v[6:9], v[158:161], v[190:193], v[6:9]
	s_barrier
	s_add_u32 s44, s44, 0x40080
	s_addc_u32 s45, s45, 0
	s_add_i32 s46, s46, s11
	v_lshl_add_u64 v[142:143], s[44:45], 0, v[134:135]
	s_mov_b32 m0, s46
	s_nop 0
	global_load_lds_dwordx4 v[142:143], off
	v_lshl_add_u64 v[142:143], s[44:45], 0, v[130:131]
	s_add_i32 m0, s46, 0x2000
	s_nop 0
	global_load_lds_dwordx4 v[142:143], off
	s_waitcnt vmcnt(6)
	s_barrier
	v_mfma_f32_16x16x32_bf16 v[58:61], v[194:197], v[162:165], v[58:61]
	v_mfma_f32_16x16x32_bf16 v[50:53], v[202:205], v[162:165], v[50:53]
	v_mfma_f32_16x16x32_bf16 v[42:45], v[194:197], v[170:173], v[42:45]
	v_mfma_f32_16x16x32_bf16 v[34:37], v[202:205], v[170:173], v[34:37]
	v_mfma_f32_16x16x32_bf16 v[26:29], v[194:197], v[178:181], v[26:29]
	v_mfma_f32_16x16x32_bf16 v[18:21], v[202:205], v[178:181], v[18:21]
	v_mfma_f32_16x16x32_bf16 v[10:13], v[194:197], v[186:189], v[10:13]
	v_mfma_f32_16x16x32_bf16 v[2:5], v[202:205], v[186:189], v[2:5]
	v_mfma_f32_16x16x32_bf16 v[58:61], v[198:201], v[166:169], v[58:61]
	v_mfma_f32_16x16x32_bf16 v[50:53], v[206:209], v[166:169], v[50:53]
	v_mfma_f32_16x16x32_bf16 v[42:45], v[198:201], v[174:177], v[42:45]
	v_mfma_f32_16x16x32_bf16 v[34:37], v[206:209], v[174:177], v[34:37]
	v_mfma_f32_16x16x32_bf16 v[26:29], v[198:201], v[182:185], v[26:29]
	v_mfma_f32_16x16x32_bf16 v[18:21], v[206:209], v[182:185], v[18:21]
	v_mfma_f32_16x16x32_bf16 v[10:13], v[198:201], v[190:193], v[10:13]
	v_mfma_f32_16x16x32_bf16 v[2:5], v[206:209], v[190:193], v[2:5]
	s_add_i32 s74, s74, 2
	s_add_u32 s26, s26, 0x100
	s_addc_u32 s27, s27, 0
	s_add_u32 s62, s62, 0x100
	s_addc_u32 s63, s63, 0
	s_cmp_gt_u32 s74, 13
	s_barrier
	s_cbranch_scc0 .LBB0_1109
	v_mul_f32_e32 v148, 0xbfb8aa3b, v126
	v_mul_f32_e32 v149, 0xbfb8aa3b, v127
	v_exp_f32_e32 v148, v148
	v_exp_f32_e32 v149, v149
	v_add_f32_e32 v148, 1.0, v148
	v_add_f32_e32 v149, 1.0, v149
	v_rcp_f32_e32 v148, v148
	v_rcp_f32_e32 v149, v149
	v_lshl_or_b32 v144, s2, 7, v157
	v_pk_mul_f32 v[126:127], v[126:127], v[148:149]
	s_movk_i32 s2, 0x1600
	v_pk_mul_f32 v[122:123], v[126:127], v[122:123]
	v_lshl_add_u32 v158, s16, 8, v156
	v_cvt_pk_bf16_f32 v122, v122, v123
	v_mul_f32_e32 v123, 0xbfb8aa3b, v128
	v_exp_f32_e32 v123, v123
	v_ashrrev_i32_e32 v145, 31, v144
	v_add_f32_e32 v123, 1.0, v123
	v_rcp_f32_e32 v126, v123
	v_mul_f32_e32 v123, 0xbfb8aa3b, v129
	v_exp_f32_e32 v123, v123
	v_mov_b64_e32 v[142:143], s[68:69]
	v_add_f32_e32 v123, 1.0, v123
	v_rcp_f32_e32 v127, v123
	s_and_b64 vcc, exec, s[38:39]
	v_pk_mul_f32 v[126:127], v[128:129], v[126:127]
	v_mad_i64_i32 v[146:147], s[26:27], v158, s2, v[142:143]
	v_pk_mul_f32 v[124:125], v[126:127], v[124:125]
	v_lshlrev_b64 v[144:145], 1, v[144:145]
	v_cvt_pk_bf16_f32 v123, v124, v125
	v_mul_f32_e32 v124, 0xbfb8aa3b, v118
	v_mul_f32_e32 v125, 0xbfb8aa3b, v119
	v_exp_f32_e32 v124, v124
	v_exp_f32_e32 v125, v125
	v_add_f32_e32 v124, 1.0, v124
	v_add_f32_e32 v125, 1.0, v125
	v_rcp_f32_e32 v124, v124
	v_rcp_f32_e32 v125, v125
	s_mov_b32 s16, s20
	v_pk_mul_f32 v[118:119], v[118:119], v[124:125]
	v_lshl_add_u64 v[146:147], v[146:147], 0, v[144:145]
	v_pk_mul_f32 v[114:115], v[118:119], v[114:115]
	s_mov_b64 s[44:45], s[28:29]
	v_cvt_pk_bf16_f32 v124, v114, v115
	v_mul_f32_e32 v114, 0xbfb8aa3b, v120
	v_mul_f32_e32 v115, 0xbfb8aa3b, v121
	v_exp_f32_e32 v114, v114
	v_exp_f32_e32 v115, v115
	v_add_f32_e32 v114, 1.0, v114
	v_add_f32_e32 v115, 1.0, v115
	v_rcp_f32_e32 v114, v114
	v_rcp_f32_e32 v115, v115
	v_mov_b32_e32 v118, 0
	v_pk_mul_f32 v[114:115], v[120:121], v[114:115]
	v_mov_b32_e32 v119, 0
	v_pk_mul_f32 v[114:115], v[114:115], v[116:117]
	v_mul_f32_e32 v116, 0xbfb8aa3b, v110
	v_mul_f32_e32 v117, 0xbfb8aa3b, v111
	v_exp_f32_e32 v116, v116
	v_exp_f32_e32 v117, v117
	v_add_f32_e32 v116, 1.0, v116
	v_add_f32_e32 v117, 1.0, v117
	v_rcp_f32_e32 v116, v116
	v_rcp_f32_e32 v117, v117
	v_cvt_pk_bf16_f32 v125, v114, v115
	v_pk_mul_f32 v[110:111], v[110:111], v[116:117]
; __device__ __forceinline__ unsigned cvt_pk_bf16(float lo, float hi) { const f32x2c f = {lo, hi}; return __builtin_bit_cast(unsigned, __builtin_convertvector(f, bf16x2c)); }
; __device__ __forceinline__ float silu_f(float g) { return g * __builtin_amdgcn_rcpf(1.0f + __expf(-g)); }
;     __device__ __forceinline__ void operator()(const f32x4 (&acc)[2][2][4][2], const Unit& u, int wr, int wc, int fr, int fq) const {
;         const int row0 = u.pm * BM + wr * 64 + fr; const int col0 = u.pn * HALF + wc * 32 + 8 * fq;
; #pragma unroll
;         for (int ai = 0; ai < 2; ++ai)
; #pragma unroll
;             for (int m = 0; m < 4; ++m) { bf16_t* rowp = H + (size_t)(row0 + ai * HALF + m * 16) * ldh + col0;
;                 const f32x4 g0 = acc[ai][0][m][0], g1 = acc[ai][0][m][1], u0 = acc[ai][1][m][0], u1 = acc[ai][1][m][1];
;                 u32x4 w; w.x = cvt_pk_bf16(silu_f(g0[0]) * u0[0], silu_f(g0[1]) * u0[1]); w.y = cvt_pk_bf16(silu_f(g0[2]) * u0[2], silu_f(g0[3]) * u0[3]);
;                 w.z = cvt_pk_bf16(silu_f(g1[0]) * u1[0], silu_f(g1[1]) * u1[1]); w.w = cvt_pk_bf16(silu_f(g1[2]) * u1[2], silu_f(g1[3]) * u1[3]);
;                 *(u32x4*)rowp = w; }
; template <class Epi, class Sched>
; __device__ __forceinline__ void gemm_phase(PG8_LAS unsigned char* lds, const Gemm g, const Sched& S, const Epi& E) {
;     ...
;         for (int a = 0; a < 2; ++a)
; #pragma unroll
;             for (int b = 0; b < 2; ++b)
; #pragma unroll
;                 for (int m = 0; m < 4; ++m)
; #pragma unroll
;                     for (int n = 0; n < 2; ++n) acc[a][b][m][n] = (f32x4){0.f, 0.f, 0.f, 0.f};
	v_or_b32_e32 v114, 16, v158
	v_pk_mul_f32 v[106:107], v[110:111], v[106:107]
	v_mad_i64_i32 v[114:115], s[26:27], v114, s2, v[142:143]
	v_cvt_pk_bf16_f32 v106, v106, v107
	v_mul_f32_e32 v107, 0xbfb8aa3b, v112
	v_exp_f32_e32 v107, v107
	v_lshl_add_u64 v[114:115], v[114:115], 0, v[144:145]
	v_add_f32_e32 v107, 1.0, v107
	v_rcp_f32_e32 v110, v107
	v_mul_f32_e32 v107, 0xbfb8aa3b, v113
	v_exp_f32_e32 v107, v107
	global_store_dwordx4 v[146:147], v[122:125], off
	v_add_f32_e32 v107, 1.0, v107
	v_rcp_f32_e32 v111, v107
	v_mov_b32_e32 v116, 0
	v_pk_mul_f32 v[110:111], v[112:113], v[110:111]
	v_mov_b32_e32 v112, 0
	v_pk_mul_f32 v[108:109], v[110:111], v[108:109]
	v_mov_b32_e32 v110, 0
	v_cvt_pk_bf16_f32 v107, v108, v109
	v_mul_f32_e32 v108, 0xbfb8aa3b, v102
	v_mul_f32_e32 v109, 0xbfb8aa3b, v103
	v_exp_f32_e32 v108, v108
	v_exp_f32_e32 v109, v109
	v_add_f32_e32 v108, 1.0, v108
	v_add_f32_e32 v109, 1.0, v109
	v_rcp_f32_e32 v108, v108
	v_rcp_f32_e32 v109, v109
	v_mov_b32_e32 v111, 0
	v_pk_mul_f32 v[102:103], v[102:103], v[108:109]
	v_mov_b32_e32 v113, 0
	v_pk_mul_f32 v[98:99], v[102:103], v[98:99]
	v_mov_b32_e32 v102, 0
	v_cvt_pk_bf16_f32 v108, v98, v99
	v_mul_f32_e32 v98, 0xbfb8aa3b, v104
	v_mul_f32_e32 v99, 0xbfb8aa3b, v105
	v_exp_f32_e32 v98, v98
	v_exp_f32_e32 v99, v99
	v_add_f32_e32 v98, 1.0, v98
	v_add_f32_e32 v99, 1.0, v99
	v_rcp_f32_e32 v98, v98
	v_rcp_f32_e32 v99, v99
	v_mov_b32_e32 v103, 0
	v_pk_mul_f32 v[98:99], v[104:105], v[98:99]
	v_mov_b32_e32 v104, 0
	v_pk_mul_f32 v[98:99], v[98:99], v[100:101]
	v_mul_f32_e32 v100, 0xbfb8aa3b, v94
	v_mul_f32_e32 v101, 0xbfb8aa3b, v95
	v_exp_f32_e32 v100, v100
	v_exp_f32_e32 v101, v101
	v_add_f32_e32 v100, 1.0, v100
	v_add_f32_e32 v101, 1.0, v101
	v_rcp_f32_e32 v100, v100
	v_rcp_f32_e32 v101, v101
	v_cvt_pk_bf16_f32 v109, v98, v99
	v_pk_mul_f32 v[94:95], v[94:95], v[100:101]
	v_or_b32_e32 v98, 32, v158
	v_pk_mul_f32 v[90:91], v[94:95], v[90:91]
	v_mad_i64_i32 v[98:99], s[26:27], v98, s2, v[142:143]
	v_cvt_pk_bf16_f32 v90, v90, v91
	v_mul_f32_e32 v91, 0xbfb8aa3b, v96
	v_exp_f32_e32 v91, v91
	v_lshl_add_u64 v[98:99], v[98:99], 0, v[144:145]
	v_add_f32_e32 v91, 1.0, v91
	v_rcp_f32_e32 v94, v91
	v_mul_f32_e32 v91, 0xbfb8aa3b, v97
	v_exp_f32_e32 v91, v91
	global_store_dwordx4 v[114:115], v[106:109], off
	v_add_f32_e32 v91, 1.0, v91
	v_rcp_f32_e32 v95, v91
	v_mov_b32_e32 v100, 0
	v_pk_mul_f32 v[94:95], v[96:97], v[94:95]
	v_mov_b32_e32 v96, 0
	v_pk_mul_f32 v[92:93], v[94:95], v[92:93]
	v_mov_b32_e32 v94, 0
	v_cvt_pk_bf16_f32 v91, v92, v93
	v_mul_f32_e32 v92, 0xbfb8aa3b, v86
	v_mul_f32_e32 v93, 0xbfb8aa3b, v87
	v_exp_f32_e32 v92, v92
	v_exp_f32_e32 v93, v93
	v_add_f32_e32 v92, 1.0, v92
	v_add_f32_e32 v93, 1.0, v93
	v_rcp_f32_e32 v92, v92
	v_rcp_f32_e32 v93, v93
	v_mov_b32_e32 v95, 0
	v_pk_mul_f32 v[86:87], v[86:87], v[92:93]
	v_mov_b32_e32 v97, 0
	v_pk_mul_f32 v[82:83], v[86:87], v[82:83]
	v_mov_b32_e32 v86, 0
	v_cvt_pk_bf16_f32 v92, v82, v83
	v_mul_f32_e32 v82, 0xbfb8aa3b, v88
	v_mul_f32_e32 v83, 0xbfb8aa3b, v89
	v_exp_f32_e32 v82, v82
	v_exp_f32_e32 v83, v83
	v_add_f32_e32 v82, 1.0, v82
	v_add_f32_e32 v83, 1.0, v83
	v_rcp_f32_e32 v82, v82
	v_rcp_f32_e32 v83, v83
	v_mov_b32_e32 v87, 0
	v_pk_mul_f32 v[82:83], v[88:89], v[82:83]
	v_mov_b32_e32 v88, 0
	v_pk_mul_f32 v[82:83], v[82:83], v[84:85]
	v_mul_f32_e32 v84, 0xbfb8aa3b, v78
	v_mul_f32_e32 v85, 0xbfb8aa3b, v79
	v_exp_f32_e32 v84, v84
	v_exp_f32_e32 v85, v85
	v_add_f32_e32 v84, 1.0, v84
	v_add_f32_e32 v85, 1.0, v85
	v_rcp_f32_e32 v84, v84
	v_rcp_f32_e32 v85, v85
	v_cvt_pk_bf16_f32 v93, v82, v83
	v_pk_mul_f32 v[78:79], v[78:79], v[84:85]
	v_or_b32_e32 v82, 48, v158
	v_pk_mul_f32 v[74:75], v[78:79], v[74:75]
	v_mad_i64_i32 v[82:83], s[26:27], v82, s2, v[142:143]
	v_cvt_pk_bf16_f32 v74, v74, v75
	v_mul_f32_e32 v75, 0xbfb8aa3b, v80
	v_exp_f32_e32 v75, v75
	v_lshl_add_u64 v[82:83], v[82:83], 0, v[144:145]
	v_add_f32_e32 v75, 1.0, v75
	v_rcp_f32_e32 v78, v75
	v_mul_f32_e32 v75, 0xbfb8aa3b, v81
	v_exp_f32_e32 v75, v75
	global_store_dwordx4 v[98:99], v[90:93], off
	v_add_f32_e32 v75, 1.0, v75
	v_rcp_f32_e32 v79, v75
	v_mov_b32_e32 v84, 0
	v_pk_mul_f32 v[78:79], v[80:81], v[78:79]
	v_mov_b32_e32 v80, 0
	v_pk_mul_f32 v[76:77], v[78:79], v[76:77]
	v_mov_b32_e32 v78, 0
	v_cvt_pk_bf16_f32 v75, v76, v77
	v_mul_f32_e32 v76, 0xbfb8aa3b, v70
	v_mul_f32_e32 v77, 0xbfb8aa3b, v71
	v_exp_f32_e32 v76, v76
	v_exp_f32_e32 v77, v77
	v_add_f32_e32 v76, 1.0, v76
	v_add_f32_e32 v77, 1.0, v77
	v_rcp_f32_e32 v76, v76
	v_rcp_f32_e32 v77, v77
	v_mov_b32_e32 v79, 0
	v_pk_mul_f32 v[70:71], v[70:71], v[76:77]
	v_mov_b32_e32 v81, 0
	v_pk_mul_f32 v[66:67], v[70:71], v[66:67]
	v_mov_b32_e32 v70, 0
	v_cvt_pk_bf16_f32 v76, v66, v67
	v_mul_f32_e32 v66, 0xbfb8aa3b, v72
	v_mul_f32_e32 v67, 0xbfb8aa3b, v73
	v_exp_f32_e32 v66, v66
	v_exp_f32_e32 v67, v67
	v_add_f32_e32 v66, 1.0, v66
	v_add_f32_e32 v67, 1.0, v67
	v_rcp_f32_e32 v66, v66
	v_rcp_f32_e32 v67, v67
	v_mov_b32_e32 v71, 0
	v_pk_mul_f32 v[66:67], v[72:73], v[66:67]
	v_mov_b32_e32 v72, 0
	v_pk_mul_f32 v[66:67], v[66:67], v[68:69]
	v_mul_f32_e32 v68, 0xbfb8aa3b, v62
	v_mul_f32_e32 v69, 0xbfb8aa3b, v63
	v_exp_f32_e32 v68, v68
	v_exp_f32_e32 v69, v69
	v_add_f32_e32 v68, 1.0, v68
	v_add_f32_e32 v69, 1.0, v69
	v_rcp_f32_e32 v68, v68
	v_rcp_f32_e32 v69, v69
	v_cvt_pk_bf16_f32 v77, v66, v67
	v_pk_mul_f32 v[62:63], v[62:63], v[68:69]
	v_add_u32_e32 v66, 0x80, v158
	v_pk_mul_f32 v[58:59], v[62:63], v[58:59]
	v_mad_i64_i32 v[66:67], s[26:27], v66, s2, v[142:143]
	v_cvt_pk_bf16_f32 v58, v58, v59
	v_mul_f32_e32 v59, 0xbfb8aa3b, v64
	v_exp_f32_e32 v59, v59
	v_lshl_add_u64 v[66:67], v[66:67], 0, v[144:145]
	v_add_f32_e32 v59, 1.0, v59
	v_rcp_f32_e32 v62, v59
; __device__ __forceinline__ unsigned cvt_pk_bf16(float lo, float hi) { const f32x2c f = {lo, hi}; return __builtin_bit_cast(unsigned, __builtin_convertvector(f, bf16x2c)); }
; __device__ __forceinline__ float silu_f(float g) { return g * __builtin_amdgcn_rcpf(1.0f + __expf(-g)); }
;     __device__ __forceinline__ void operator()(const f32x4 (&acc)[2][2][4][2], const Unit& u, int wr, int wc, int fr, int fq) const {
;         const int row0 = u.pm * BM + wr * 64 + fr; const int col0 = u.pn * HALF + wc * 32 + 8 * fq;
; #pragma unroll
;         for (int ai = 0; ai < 2; ++ai)
; #pragma unroll
;             for (int m = 0; m < 4; ++m) { bf16_t* rowp = H + (size_t)(row0 + ai * HALF + m * 16) * ldh + col0;
;                 const f32x4 g0 = acc[ai][0][m][0], g1 = acc[ai][0][m][1], u0 = acc[ai][1][m][0], u1 = acc[ai][1][m][1];
;                 u32x4 w; w.x = cvt_pk_bf16(silu_f(g0[0]) * u0[0], silu_f(g0[1]) * u0[1]); w.y = cvt_pk_bf16(silu_f(g0[2]) * u0[2], silu_f(g0[3]) * u0[3]);
;                 w.z = cvt_pk_bf16(silu_f(g1[0]) * u1[0], silu_f(g1[1]) * u1[1]); w.w = cvt_pk_bf16(silu_f(g1[2]) * u1[2], silu_f(g1[3]) * u1[3]);
;                 *(u32x4*)rowp = w; }
; template <class Epi, class Sched>
; __device__ __forceinline__ void gemm_phase(PG8_LAS unsigned char* lds, const Gemm g, const Sched& S, const Epi& E) {
;     ...
;         for (int a = 0; a < 2; ++a)
; #pragma unroll
;             for (int b = 0; b < 2; ++b)
; #pragma unroll
;                 for (int m = 0; m < 4; ++m)
; #pragma unroll
;                     for (int n = 0; n < 2; ++n) acc[a][b][m][n] = (f32x4){0.f, 0.f, 0.f, 0.f};
	v_mul_f32_e32 v59, 0xbfb8aa3b, v65
	v_exp_f32_e32 v59, v59
	global_store_dwordx4 v[82:83], v[74:77], off
	v_add_f32_e32 v59, 1.0, v59
	v_rcp_f32_e32 v63, v59
	v_mov_b32_e32 v68, 0
	v_pk_mul_f32 v[62:63], v[64:65], v[62:63]
	v_mov_b32_e32 v64, 0
	v_pk_mul_f32 v[60:61], v[62:63], v[60:61]
	v_mov_b32_e32 v62, 0
	v_cvt_pk_bf16_f32 v59, v60, v61
	v_mul_f32_e32 v60, 0xbfb8aa3b, v54
	v_mul_f32_e32 v61, 0xbfb8aa3b, v55
	v_exp_f32_e32 v60, v60
	v_exp_f32_e32 v61, v61
	v_add_f32_e32 v60, 1.0, v60
	v_add_f32_e32 v61, 1.0, v61
	v_rcp_f32_e32 v60, v60
	v_rcp_f32_e32 v61, v61
	v_mov_b32_e32 v63, 0
	v_pk_mul_f32 v[54:55], v[54:55], v[60:61]
	v_mov_b32_e32 v65, 0
	v_pk_mul_f32 v[50:51], v[54:55], v[50:51]
	v_mov_b32_e32 v54, 0
	v_cvt_pk_bf16_f32 v60, v50, v51
	v_mul_f32_e32 v50, 0xbfb8aa3b, v56
	v_mul_f32_e32 v51, 0xbfb8aa3b, v57
	v_exp_f32_e32 v50, v50
	v_exp_f32_e32 v51, v51
	v_add_f32_e32 v50, 1.0, v50
	v_add_f32_e32 v51, 1.0, v51
	v_rcp_f32_e32 v50, v50
	v_rcp_f32_e32 v51, v51
	v_mov_b32_e32 v55, 0
	v_pk_mul_f32 v[50:51], v[56:57], v[50:51]
	v_mov_b32_e32 v56, 0
	v_pk_mul_f32 v[50:51], v[50:51], v[52:53]
	v_mul_f32_e32 v52, 0xbfb8aa3b, v46
	v_mul_f32_e32 v53, 0xbfb8aa3b, v47
	v_exp_f32_e32 v52, v52
	v_exp_f32_e32 v53, v53
	v_add_f32_e32 v52, 1.0, v52
	v_add_f32_e32 v53, 1.0, v53
	v_rcp_f32_e32 v52, v52
	v_rcp_f32_e32 v53, v53
	v_cvt_pk_bf16_f32 v61, v50, v51
	v_pk_mul_f32 v[46:47], v[46:47], v[52:53]
	v_add_u32_e32 v50, 0x90, v158
	v_pk_mul_f32 v[42:43], v[46:47], v[42:43]
	v_mad_i64_i32 v[50:51], s[26:27], v50, s2, v[142:143]
	v_cvt_pk_bf16_f32 v42, v42, v43
	v_mul_f32_e32 v43, 0xbfb8aa3b, v48
	v_exp_f32_e32 v43, v43
	v_lshl_add_u64 v[50:51], v[50:51], 0, v[144:145]
	v_add_f32_e32 v43, 1.0, v43
	v_rcp_f32_e32 v46, v43
	v_mul_f32_e32 v43, 0xbfb8aa3b, v49
	v_exp_f32_e32 v43, v43
	global_store_dwordx4 v[66:67], v[58:61], off
	v_add_f32_e32 v43, 1.0, v43
	v_rcp_f32_e32 v47, v43
	v_mov_b32_e32 v52, 0
	v_pk_mul_f32 v[46:47], v[48:49], v[46:47]
	v_mov_b32_e32 v48, 0
	v_pk_mul_f32 v[44:45], v[46:47], v[44:45]
	v_mov_b32_e32 v46, 0
	v_cvt_pk_bf16_f32 v43, v44, v45
	v_mul_f32_e32 v44, 0xbfb8aa3b, v38
	v_mul_f32_e32 v45, 0xbfb8aa3b, v39
	v_exp_f32_e32 v44, v44
	v_exp_f32_e32 v45, v45
	v_add_f32_e32 v44, 1.0, v44
	v_add_f32_e32 v45, 1.0, v45
	v_rcp_f32_e32 v44, v44
	v_rcp_f32_e32 v45, v45
	v_mov_b32_e32 v47, 0
	v_pk_mul_f32 v[38:39], v[38:39], v[44:45]
	v_mov_b32_e32 v49, 0
	v_pk_mul_f32 v[34:35], v[38:39], v[34:35]
	v_mov_b32_e32 v38, 0
	v_cvt_pk_bf16_f32 v44, v34, v35
	v_mul_f32_e32 v34, 0xbfb8aa3b, v40
	v_mul_f32_e32 v35, 0xbfb8aa3b, v41
	v_exp_f32_e32 v34, v34
	v_exp_f32_e32 v35, v35
	v_add_f32_e32 v34, 1.0, v34
	v_add_f32_e32 v35, 1.0, v35
	v_rcp_f32_e32 v34, v34
	v_rcp_f32_e32 v35, v35
	v_mov_b32_e32 v39, 0
	v_pk_mul_f32 v[34:35], v[40:41], v[34:35]
	v_mov_b32_e32 v40, 0
	v_pk_mul_f32 v[34:35], v[34:35], v[36:37]
	v_mul_f32_e32 v36, 0xbfb8aa3b, v30
	v_mul_f32_e32 v37, 0xbfb8aa3b, v31
	v_exp_f32_e32 v36, v36
	v_exp_f32_e32 v37, v37
	v_add_f32_e32 v36, 1.0, v36
	v_add_f32_e32 v37, 1.0, v37
	v_rcp_f32_e32 v36, v36
	v_rcp_f32_e32 v37, v37
	v_cvt_pk_bf16_f32 v45, v34, v35
	v_pk_mul_f32 v[30:31], v[30:31], v[36:37]
	v_add_u32_e32 v34, 0xa0, v158
	v_pk_mul_f32 v[26:27], v[30:31], v[26:27]
	v_mad_i64_i32 v[34:35], s[26:27], v34, s2, v[142:143]
	v_cvt_pk_bf16_f32 v26, v26, v27
	v_mul_f32_e32 v27, 0xbfb8aa3b, v32
	v_exp_f32_e32 v27, v27
	global_store_dwordx4 v[50:51], v[42:45], off
	v_add_f32_e32 v27, 1.0, v27
	v_rcp_f32_e32 v30, v27
	v_mul_f32_e32 v27, 0xbfb8aa3b, v33
	v_exp_f32_e32 v27, v27
	v_lshl_add_u64 v[34:35], v[34:35], 0, v[144:145]
	v_add_f32_e32 v27, 1.0, v27
	v_rcp_f32_e32 v31, v27
	v_mov_b32_e32 v36, 0
	v_pk_mul_f32 v[30:31], v[32:33], v[30:31]
	v_mov_b32_e32 v32, 0
	v_pk_mul_f32 v[28:29], v[30:31], v[28:29]
	v_mov_b32_e32 v30, 0
	v_cvt_pk_bf16_f32 v27, v28, v29
	v_mul_f32_e32 v28, 0xbfb8aa3b, v22
	v_mul_f32_e32 v29, 0xbfb8aa3b, v23
	v_exp_f32_e32 v28, v28
	v_exp_f32_e32 v29, v29
	v_add_f32_e32 v28, 1.0, v28
	v_add_f32_e32 v29, 1.0, v29
	v_rcp_f32_e32 v28, v28
	v_rcp_f32_e32 v29, v29
	v_mov_b32_e32 v31, 0
	v_pk_mul_f32 v[22:23], v[22:23], v[28:29]
; __device__ __forceinline__ unsigned cvt_pk_bf16(float lo, float hi) { const f32x2c f = {lo, hi}; return __builtin_bit_cast(unsigned, __builtin_convertvector(f, bf16x2c)); }
; __device__ __forceinline__ float silu_f(float g) { return g * __builtin_amdgcn_rcpf(1.0f + __expf(-g)); }
;     __device__ __forceinline__ void operator()(const f32x4 (&acc)[2][2][4][2], const Unit& u, int wr, int wc, int fr, int fq) const {
;         const int row0 = u.pm * BM + wr * 64 + fr; const int col0 = u.pn * HALF + wc * 32 + 8 * fq;
; #pragma unroll
;         for (int ai = 0; ai < 2; ++ai)
; #pragma unroll
;             for (int m = 0; m < 4; ++m) { bf16_t* rowp = H + (size_t)(row0 + ai * HALF + m * 16) * ldh + col0;
;                 const f32x4 g0 = acc[ai][0][m][0], g1 = acc[ai][0][m][1], u0 = acc[ai][1][m][0], u1 = acc[ai][1][m][1];
;                 u32x4 w; w.x = cvt_pk_bf16(silu_f(g0[0]) * u0[0], silu_f(g0[1]) * u0[1]); w.y = cvt_pk_bf16(silu_f(g0[2]) * u0[2], silu_f(g0[3]) * u0[3]);
;                 w.z = cvt_pk_bf16(silu_f(g1[0]) * u1[0], silu_f(g1[1]) * u1[1]); w.w = cvt_pk_bf16(silu_f(g1[2]) * u1[2], silu_f(g1[3]) * u1[3]);
;                 *(u32x4*)rowp = w; }
; template <class Epi, class Sched>
; __device__ __forceinline__ void gemm_phase(PG8_LAS unsigned char* lds, const Gemm g, const Sched& S, const Epi& E) {
;     ...
;         for (int a = 0; a < 2; ++a)
; #pragma unroll
;             for (int b = 0; b < 2; ++b)
; #pragma unroll
;                 for (int m = 0; m < 4; ++m)
; #pragma unroll
;                     for (int n = 0; n < 2; ++n) acc[a][b][m][n] = (f32x4){0.f, 0.f, 0.f, 0.f};
	v_mov_b32_e32 v33, 0
	v_pk_mul_f32 v[18:19], v[22:23], v[18:19]
	v_mov_b32_e32 v22, 0
	v_cvt_pk_bf16_f32 v28, v18, v19
	v_mul_f32_e32 v18, 0xbfb8aa3b, v24
	v_mul_f32_e32 v19, 0xbfb8aa3b, v25
	v_exp_f32_e32 v18, v18
	v_exp_f32_e32 v19, v19
	v_add_f32_e32 v18, 1.0, v18
	v_add_f32_e32 v19, 1.0, v19
	v_rcp_f32_e32 v18, v18
	v_rcp_f32_e32 v19, v19
	v_mov_b32_e32 v23, 0
	v_pk_mul_f32 v[18:19], v[24:25], v[18:19]
	v_mov_b32_e32 v24, 0
	v_pk_mul_f32 v[18:19], v[18:19], v[20:21]
	v_mul_f32_e32 v20, 0xbfb8aa3b, v14
	v_mul_f32_e32 v21, 0xbfb8aa3b, v15
	v_exp_f32_e32 v20, v20
	v_exp_f32_e32 v21, v21
	v_add_f32_e32 v20, 1.0, v20
	v_add_f32_e32 v21, 1.0, v21
	v_rcp_f32_e32 v20, v20
	v_rcp_f32_e32 v21, v21
	v_cvt_pk_bf16_f32 v29, v18, v19
	v_pk_mul_f32 v[14:15], v[14:15], v[20:21]
	v_add_u32_e32 v18, 0xb0, v158
	v_pk_mul_f32 v[10:11], v[14:15], v[10:11]
	v_mad_i64_i32 v[18:19], s[26:27], v18, s2, v[142:143]
	v_cvt_pk_bf16_f32 v10, v10, v11
	v_mul_f32_e32 v11, 0xbfb8aa3b, v16
	v_exp_f32_e32 v11, v11
	s_mov_b32 s2, s18
	v_add_f32_e32 v11, 1.0, v11
	v_rcp_f32_e32 v14, v11
	v_mul_f32_e32 v11, 0xbfb8aa3b, v17
	v_exp_f32_e32 v11, v11
	s_mov_b64 s[26:27], s[24:25]
	v_add_f32_e32 v11, 1.0, v11
	v_rcp_f32_e32 v15, v11
	v_lshl_add_u64 v[18:19], v[18:19], 0, v[144:145]
	v_pk_mul_f32 v[14:15], v[16:17], v[14:15]
	global_store_dwordx4 v[34:35], v[26:29], off
	v_pk_mul_f32 v[12:13], v[14:15], v[12:13]
	v_mov_b32_e32 v14, 0
	v_cvt_pk_bf16_f32 v11, v12, v13
	v_mul_f32_e32 v12, 0xbfb8aa3b, v6
	v_mul_f32_e32 v13, 0xbfb8aa3b, v7
	v_exp_f32_e32 v12, v12
	v_exp_f32_e32 v13, v13
	v_add_f32_e32 v12, 1.0, v12
	v_add_f32_e32 v13, 1.0, v13
	v_rcp_f32_e32 v12, v12
	v_rcp_f32_e32 v13, v13
	v_mov_b32_e32 v15, 0
	v_pk_mul_f32 v[6:7], v[6:7], v[12:13]
	v_mov_b32_e32 v16, 0
	v_pk_mul_f32 v[2:3], v[6:7], v[2:3]
	v_mov_b32_e32 v6, 0
	v_cvt_pk_bf16_f32 v12, v2, v3
	v_mul_f32_e32 v2, 0xbfb8aa3b, v8
	v_mul_f32_e32 v3, 0xbfb8aa3b, v9
	v_exp_f32_e32 v2, v2
	v_exp_f32_e32 v3, v3
	v_add_f32_e32 v2, 1.0, v2
	v_add_f32_e32 v3, 1.0, v3
	v_rcp_f32_e32 v2, v2
	v_rcp_f32_e32 v3, v3
	v_mov_b32_e32 v7, 0
	v_pk_mul_f32 v[2:3], v[8:9], v[2:3]
	v_mov_b32_e32 v8, 0
	v_pk_mul_f32 v[2:3], v[2:3], v[4:5]
	v_mov_b32_e32 v4, 0
	v_cvt_pk_bf16_f32 v13, v2, v3
	global_store_dwordx4 v[18:19], v[10:13], off
	v_mov_b32_e32 v5, 0
	v_mov_b32_e32 v9, 0
	v_mov_b32_e32 v10, 0
	v_mov_b32_e32 v11, 0
	v_mov_b32_e32 v12, 0
	v_mov_b32_e32 v13, 0
	v_mov_b32_e32 v17, 0
	v_mov_b32_e32 v18, 0
	v_mov_b32_e32 v19, 0
	v_mov_b32_e32 v20, 0
	v_mov_b32_e32 v21, 0
	v_mov_b32_e32 v25, 0
	v_mov_b32_e32 v26, 0
	v_mov_b32_e32 v27, 0
	v_mov_b32_e32 v28, 0
	v_mov_b32_e32 v29, 0
	v_mov_b32_e32 v34, 0
	v_mov_b32_e32 v35, 0
	v_mov_b32_e32 v37, 0
	v_mov_b32_e32 v41, 0
	v_mov_b32_e32 v42, 0
	v_mov_b32_e32 v43, 0
	v_mov_b32_e32 v44, 0
	v_mov_b32_e32 v45, 0
	v_mov_b32_e32 v50, 0
	v_mov_b32_e32 v51, 0
	v_mov_b32_e32 v53, 0
	v_mov_b32_e32 v57, 0
	v_mov_b32_e32 v58, 0
	v_mov_b32_e32 v59, 0
	v_mov_b32_e32 v60, 0
	v_mov_b32_e32 v61, 0
	v_mov_b32_e32 v66, 0
	v_mov_b32_e32 v67, 0
	v_mov_b32_e32 v69, 0
	v_mov_b32_e32 v73, 0
	v_mov_b32_e32 v74, 0
	v_mov_b32_e32 v75, 0
	v_mov_b32_e32 v76, 0
	v_mov_b32_e32 v77, 0
	v_mov_b32_e32 v82, 0
	v_mov_b32_e32 v83, 0
	v_mov_b32_e32 v85, 0
	v_mov_b32_e32 v89, 0
	v_mov_b32_e32 v90, 0
	v_mov_b32_e32 v91, 0
	v_mov_b32_e32 v92, 0
	v_mov_b32_e32 v93, 0
	v_mov_b32_e32 v98, 0
	v_mov_b32_e32 v99, 0
	v_mov_b32_e32 v101, 0
	v_mov_b32_e32 v105, 0
	v_mov_b32_e32 v106, 0
	v_mov_b32_e32 v107, 0
	v_mov_b32_e32 v108, 0
	v_mov_b32_e32 v109, 0
	v_mov_b32_e32 v114, 0
	v_mov_b32_e32 v115, 0
	v_mov_b32_e32 v117, 0
	v_mov_b32_e32 v120, 0
	v_mov_b32_e32 v121, 0
	v_mov_b32_e32 v122, 0
	v_mov_b32_e32 v123, 0
	v_mov_b32_e32 v124, 0
	v_mov_b32_e32 v125, 0
	v_mov_b32_e32 v126, 0
	v_mov_b32_e32 v127, 0
	v_mov_b32_e32 v128, 0
	v_mov_b32_e32 v129, 0
	s_cbranch_vccz .LBB0_1106
	s_waitcnt vmcnt(0)
	v_readlane_b32 s12, v255, 32
	v_readlane_b32 s52, v255, 35
	v_readlane_b32 s60, v255, 37
	s_cmpk_gt_u32 s8, 0xff
	v_readlane_b32 s13, v255, 33
	v_readlane_b32 s53, v255, 36
	v_readlane_b32 s61, v255, 38
	s_cbranch_scc1 .LBB0_1113
	s_barrier
